# FFN-up epilogue: conv weights prefetched per tile into a per-wave LDS slot by one LDS-DMA load at the tile top, read back by ds_read; K-loop head drain removed
# speedup vs baseline: 1.0249x; 1.0045x over previous
; #define PG8_STAGE(bufoff, gbase, voff) do { _Pragma("unroll") for (int _i = 0; _i < 2; ++_i) \
;         __builtin_amdgcn_global_load_lds((const unsigned*)((const char*)(gbase) + (voff)[_i]), (PG8_LAS unsigned*)(lds + (bufoff) + ldsw + _i * 8192), 16, 0, 0); } while (0)
; #define PG8_WAIT_V(n) asm volatile("s_waitcnt vmcnt(" #n ")" ::: "memory")
; #define PG8_BAR __builtin_amdgcn_s_barrier()
; template <class Epi, class Sched, bool ALIGN_EPI = false, bool SP2 = false, bool AROWS128 = false>
; __device__ __forceinline__ void gemm_phase(PG8_LAS unsigned char* lds, const Gemm g, const Sched& S, const Epi& E) {
;     int tid_ = threadIdx.x; asm volatile("" : "+v"(tid_)); const int tid = tid_, wid = __builtin_amdgcn_readfirstlane(tid >> 6), lane = tid & 63, wr = wid >> 2, wc = wid & 3, fr = lane & 15, fq = lane >> 4;
;     const int K = g.K, nt = K / BK;
;     unsigned voffA[2], voffB[2];
; #pragma unroll
;     for (int i = 0; i < 2; ++i) { int R, C; stage_rc(tid * 16 + i * 8192, R, C); const int Rb = Epi::PERM ? ((R & ~31) + perm32(R & 31)) : R;
;         const int Ra = AROWS128 ? (128 * (R >> 6) + (R & 63)) : R;
;         voffA[i] = (unsigned)(Ra * K + C) * 2u; voffB[i] = (unsigned)(Rb * K + C) * 2u; }
;     const size_t kstep = (size_t)(BK * 2);
;     const size_t hstep = (size_t)HALF * K * 2;
;     const size_t tstep = 2 * hstep;
;     const size_t hstepA = AROWS128 ? hstep / 2 : hstep;
;     const unsigned ldsw = (unsigned)wid * 1024u;
;     const int aoff = lds_byte(wr * 64 + fr, fq * 8), boff = lds_byte(wc * 32 + fr, fq * 8);
;     ...
;         PG8_STAGE(PG8_SB(0, 0), cB, voffB); PG8_STAGE(PG8_SB(0, 1), cB + hstep, voffB); PG8_STAGE(PG8_SA(0, 0), cA, voffA); PG8_STAGE(PG8_SA(0, 1), cA + hstepA, voffA);
;         if (wr == 1) PG8_BAR;
;         PG8_WAIT_V(2); PG8_BAR;
;         PG8_STAGE(PG8_SB(1, 0), cB + kstep, voffB); PG8_STAGE(PG8_SA(1, 0), cA + kstep, voffA); PG8_STAGE(PG8_SB(1, 1), cB + hstep + kstep, voffB);
;         PG8_WAIT_V(6); PG8_BAR;
.LBB0_620:
	s_lshl_b32 s0, s0, 5
	s_mov_b64 s[26:27], 0x80
	s_and_b32 s14, s0, 0x60
	s_add_i32 m0, s84, 0x18000
	v_lshl_add_u64 v[6:7], v[6:7], 0, s[26:27]
	s_lshl_b32 s4, s12, 13
	s_lshl_b32 s5, s14, 7
	s_waitcnt vmcnt(2)
	s_barrier
	global_load_lds_dwordx4 v[6:7], off
	v_lshl_add_u64 v[4:5], v[4:5], 0, s[26:27]
	s_add_i32 m0, s84, 0x1a000
	s_add_i32 s89, s84, 0x8000
	s_add_i32 s90, s84, 0xa000
	global_load_lds_dwordx4 v[4:5], off
	v_lshl_add_u64 v[0:1], v[0:1], 0, s[26:27]
	s_mov_b32 m0, s89
	s_add_u32 s0, s20, 0x40080
	global_load_lds_dwordx4 v[0:1], off
	v_lshl_add_u64 v[0:1], v[2:3], 0, s[26:27]
	s_mov_b32 m0, s90
	s_addc_u32 s1, s21, 0
	global_load_lds_dwordx4 v[0:1], off
	s_add_i32 m0, s84, 0x1c000
	v_lshl_add_u64 v[0:1], s[0:1], 0, v[162:163]
	global_load_lds_dwordx4 v[0:1], off
	v_lshl_add_u64 v[0:1], s[0:1], 0, v[166:167]
	s_add_i32 m0, s84, 0x1e000
	v_lshlrev_b32_e32 v3, 2, v8
	global_load_lds_dwordx4 v[0:1], off
	v_and_b32_e32 v0, 15, v8
	v_lshrrev_b32_e32 v1, 1, v8
	v_and_b32_e32 v1, 24, v1
	v_lshlrev_b32_e32 v2, 6, v0
	v_lshl_or_b32 v2, v1, 1, v2
	v_and_b32_e32 v3, 32, v3
	v_bitop3_b32 v4, v2, s4, v3 bitop3:0xde
	v_bitop3_b32 v200, v2, s5, v3 bitop3:0xde
	v_and_b32_e32 v2, 3, v8
	v_lshl_or_b32 v201, s12, 7, v0
	v_cmp_eq_u32_e64 s[0:1], 15, v0
	v_cmp_eq_u32_e64 s[4:5], 0, v0
	v_cmp_eq_u32_e64 s[6:7], 1, v2
	v_cmp_eq_u32_e64 s[8:9], 2, v2
	v_add_u32_e32 v2, -1, v2
	v_cmp_ne_u32_e64 s[10:11], 15, v0
	v_cmp_gt_u32_e64 s[12:13], 4, v0
	v_cmp_ne_u32_e64 s[36:37], 0, v0
	v_lshlrev_b32_e32 v0, 5, v201
	s_cmpk_lt_u32 s3, 0x100
	v_cmp_gt_u32_e64 s[30:31], 2, v2
	v_add_u32_e32 v203, 0xffe80000, v0
	v_add_u32_e32 v205, 0xffe80800, v0
	v_lshlrev_b32_e32 v0, 11, v11
	v_and_b32_e32 v2, 1, v9
	s_cselect_b64 s[28:29], -1, 0
	s_ashr_i32 s92, s74, 31
	s_ashr_i32 s94, s2, 31
	v_or_b32_e32 v206, s14, v1
	v_and_b32_e32 v0, 0xfffc0000, v0
	v_lshlrev_b32_e32 v1, 11, v12
	v_lshlrev_b32_e32 v2, 6, v2
	s_add_u32 s38, s60, 0x4000
	v_or3_b32 v0, v0, v1, v2
	s_addc_u32 s39, s61, 0
	v_lshl_add_u32 v168, v10, 1, v0
	v_lshlrev_b32_e32 v0, 11, v15
	v_and_b32_e32 v2, 1, v13
	s_waitcnt vmcnt(6)
	s_add_u32 s50, s60, 0x8000
	v_and_b32_e32 v0, 0xfffc0000, v0
	v_lshlrev_b32_e32 v1, 11, v16
	v_lshlrev_b32_e32 v2, 6, v2
	s_addc_u32 s51, s61, 0
	v_or3_b32 v0, v0, v1, v2
	s_add_i32 s3, 0, 0x10000
	s_add_i32 s95, 0, 0x14000
	s_movk_i32 s91, 0x100
	s_mov_b32 s93, s74
	v_add_u32_e32 v202, 0xffff4000, v201
	v_add_u32_e32 v204, 0xffff4040, v201
	v_mov_b32_e32 v169, v163
	v_lshl_add_u32 v170, v14, 1, v0
	v_mov_b32_e32 v171, v163
	v_mov_b64_e32 v[172:173], 0x18c0
	v_mov_b64_e32 v[174:175], 0x18bf
	v_add_u32_e32 v207, s3, v200
	v_add_u32_e32 v208, s95, v200
	v_add_u32_e32 v209, 0, v4
	s_mov_b32 s96, 0x2aaaaaab
	s_mov_b32 s97, 0x3d372713
	v_mbcnt_lo_u32_b32 v232, -1, 0
	v_mbcnt_hi_u32_b32 v232, -1, v232
	v_and_b32_e32 v233, 7, v232
	v_lshlrev_b32_e32 v233, 4, v233
	v_lshrrev_b32_e32 v235, 5, v206
	v_lshl_add_u32 v233, v235, 7, v233
	v_bfe_u32 v235, v232, 3, 2
	v_mov_b32_e32 v230, s60
	v_mov_b32_e32 v231, s61
	v_cmp_eq_u32_e32 vcc, 1, v235
	v_mov_b32_e32 v236, s38
	v_mov_b32_e32 v237, s39
	v_cndmask_b32_e32 v230, v230, v236, vcc
	v_cndmask_b32_e32 v231, v231, v237, vcc
	v_cmp_eq_u32_e32 vcc, 2, v235
	v_mov_b32_e32 v236, s50
	v_mov_b32_e32 v237, s51
	v_cndmask_b32_e32 v230, v230, v236, vcc
	v_cndmask_b32_e32 v231, v231, v237, vcc
	v_cmp_eq_u32_e32 vcc, 3, v235
	v_mov_b32_e32 v236, s62
	v_mov_b32_e32 v237, s63
	v_cndmask_b32_e32 v230, v230, v236, vcc
	v_cndmask_b32_e32 v231, v231, v237, vcc
	v_mov_b32_e32 v236, v233
	v_mov_b32_e32 v237, 0
	v_lshl_add_u64 v[230:231], v[230:231], 0, v[236:237]
	s_lshr_b32 s100, s84, 1
	s_add_i32 s100, s100, 0x21000
	v_bfe_u32 v234, v206, 3, 2
	v_lshlrev_b32_e32 v234, 5, v234
	v_add_u32_e32 v234, s100, v234
	s_barrier
	s_branch .LBB0_623

;     __device__ __forceinline__ void operator()(const f32x4 (&acc)[2][2][4][2], const Unit& u, int wr, int wc, int fr, int fq) const {
;     ...
;         for (int n = 0; n < 2; ++n) { w0[n] = *(const f32x4*)(cw + ch0 + 4 * n); w1[n] = *(const f32x4*)(cw + 4096 + ch0 + 4 * n); w2[n] = *(const f32x4*)(cw + 8192 + ch0 + 4 * n); bb[n] = *(const f32x4*)(cb + ch0 + 4 * n); }
; template <class Epi, class Sched, bool ALIGN_EPI = false, bool SP2 = false, bool AROWS128 = false>
; __device__ __forceinline__ void gemm_phase(PG8_LAS unsigned char* lds, const Gemm g, const Sched& S, const Epi& E) {
;     ...
; #pragma unroll
;         for (int a = 0; a < 2; ++a)
; #pragma unroll
;             for (int b = 0; b < 2; ++b)
; #pragma unroll
;                 for (int m = 0; m < 4; ++m)
; #pragma unroll
;                     for (int n = 0; n < 2; ++n) acc[a][b][m][n] = (f32x4){0.f, 0.f, 0.f, 0.f};
;         cur = nxt; cA = nA; cB = nB; ++ui;
.LBB0_625:
	s_lshl_b32 s98, s16, 9
	s_mov_b32 s99, 0
	v_lshl_add_u64 v[232:233], s[98:99], 0, v[230:231]
	s_mov_b32 m0, s100
	s_mov_b32 exec_hi, 0
	global_load_lds_dwordx4 v[232:233], off
	s_mov_b32 exec_hi, -1
	s_ashr_i32 s55, s54, 31
	s_lshl_b64 s[56:57], s[54:55], 19
	s_add_u32 s56, s46, s56
	s_addc_u32 s57, s47, s57
	s_and_b64 s[58:59], s[14:15], exec
	s_cselect_b32 s17, s57, s19
	s_cselect_b32 s33, s56, s18
	s_ashr_i32 s53, s52, 31
	s_lshl_b64 s[58:59], s[52:53], 19
	s_add_u32 s58, s78, s58
	s_addc_u32 s59, s79, s59
	s_and_b64 s[72:73], s[14:15], exec
	s_cselect_b32 s53, s59, s21
	s_cselect_b32 s55, s58, s20
	s_add_u32 s18, s18, 0x20080
	s_addc_u32 s19, s19, 0
	s_add_u32 s65, s20, 0x100
	v_mov_b32_e32 v0, 0
	s_addc_u32 s72, s21, 0
	s_mov_b32 s73, -2
	v_mov_b64_e32 v[0:1], 0
	v_mov_b64_e32 v[2:3], 0
	v_mov_b64_e32 v[4:5], 0
	v_mov_b64_e32 v[6:7], 0
	v_mov_b64_e32 v[8:9], 0
	v_mov_b64_e32 v[10:11], 0
	v_mov_b64_e32 v[12:13], 0
	v_mov_b64_e32 v[14:15], 0
	v_mov_b64_e32 v[16:17], 0
	v_mov_b64_e32 v[18:19], 0
	v_mov_b64_e32 v[20:21], 0
	v_mov_b64_e32 v[22:23], 0
	v_mov_b64_e32 v[24:25], 0
	v_mov_b64_e32 v[26:27], 0
	v_mov_b64_e32 v[28:29], 0
	v_mov_b64_e32 v[30:31], 0
	v_mov_b64_e32 v[32:33], 0
	v_mov_b64_e32 v[34:35], 0
	v_mov_b64_e32 v[36:37], 0
	v_mov_b64_e32 v[38:39], 0
	v_mov_b64_e32 v[40:41], 0
	v_mov_b64_e32 v[42:43], 0
	v_mov_b64_e32 v[44:45], 0
	v_mov_b64_e32 v[46:47], 0
	v_mov_b64_e32 v[48:49], 0
	v_mov_b64_e32 v[50:51], 0
	v_mov_b64_e32 v[52:53], 0
	v_mov_b64_e32 v[54:55], 0
	v_mov_b64_e32 v[56:57], 0
	v_mov_b64_e32 v[58:59], 0
	v_mov_b64_e32 v[60:61], 0
	v_mov_b64_e32 v[62:63], 0
	v_mov_b64_e32 v[64:65], 0
	v_mov_b64_e32 v[66:67], 0
	v_mov_b64_e32 v[68:69], 0
	v_mov_b64_e32 v[70:71], 0
	v_mov_b64_e32 v[104:105], 0
	v_mov_b64_e32 v[106:107], 0
	v_mov_b64_e32 v[108:109], 0
	v_mov_b64_e32 v[110:111], 0
	v_mov_b64_e32 v[112:113], 0
	v_mov_b64_e32 v[114:115], 0
	v_mov_b64_e32 v[116:117], 0
	v_mov_b64_e32 v[118:119], 0
	v_mov_b64_e32 v[120:121], 0
	v_mov_b64_e32 v[122:123], 0
	v_mov_b64_e32 v[124:125], 0
	v_mov_b64_e32 v[126:127], 0
	v_mov_b64_e32 v[128:129], 0
	v_mov_b64_e32 v[130:131], 0
	v_mov_b64_e32 v[132:133], 0
	v_mov_b64_e32 v[134:135], 0
	v_mov_b64_e32 v[136:137], 0
	v_mov_b64_e32 v[138:139], 0
	v_mov_b64_e32 v[140:141], 0
	v_mov_b64_e32 v[142:143], 0
	v_mov_b64_e32 v[144:145], 0
	v_mov_b64_e32 v[146:147], 0
	v_mov_b64_e32 v[148:149], 0
	v_mov_b64_e32 v[150:151], 0
	v_mov_b64_e32 v[152:153], 0
	v_mov_b64_e32 v[154:155], 0
	v_mov_b64_e32 v[156:157], 0
	v_mov_b64_e32 v[158:159], 0

;     __device__ __forceinline__ void operator()(const f32x4 (&acc)[2][2][4][2], const Unit& u, int wr, int wc, int fr, int fq) const {
;         const bool fix = u.pm >= nmain;
;         const int ch0 = u.pn * 128 + wc * 32 + 8 * fq;
;         f32x4 w0[2], w1[2], w2[2], bb[2];
; #pragma unroll
;         for (int n = 0; n < 2; ++n) { w0[n] = *(const f32x4*)(cw + ch0 + 4 * n); w1[n] = *(const f32x4*)(cw + 4096 + ch0 + 4 * n); w2[n] = *(const f32x4*)(cw + 8192 + ch0 + 4 * n); bb[n] = *(const f32x4*)(cb + ch0 + 4 * n); }
.LBB0_629:
	v_lshl_or_b32 v176, s16, 7, v206
	v_ashrrev_i32_e32 v177, 31, v176
	ds_read_b128 v[88:91], v234
	ds_read_b128 v[72:75], v234 offset:16
	ds_read_b128 v[92:95], v234 offset:128
	ds_read_b128 v[76:79], v234 offset:144
	ds_read_b128 v[96:99], v234 offset:256
	ds_read_b128 v[80:83], v234 offset:272
	ds_read_b128 v[100:103], v234 offset:384
	ds_read_b128 v[84:87], v234 offset:400
	s_cmpk_lt_i32 s64, 0xc0
	s_cselect_b64 s[18:19], -1, 0
	s_cmpk_gt_i32 s64, 0xbf
	s_cselect_b64 s[80:81], -1, 0
	s_lshl_b32 s33, s64, 8
	v_add_u32_e32 v211, s33, v201
	v_mov_b32_e32 v180, 1.0
	s_and_b64 vcc, exec, s[18:19]
	s_mov_b64 s[82:83], s[36:37]
	v_mov_b32_e32 v182, 1.0
	v_mov_b32_e32 v178, v211
	s_cbranch_vccnz .LBB0_631
	v_add_u32_e32 v178, s33, v202
	v_ashrrev_i32_e32 v178, 2, v178
	v_cmp_eq_u32_e32 vcc, s91, v178
	v_cndmask_b32_e64 v180, 0, 1, s[12:13]
	s_and_b64 s[20:21], s[30:31], exec
	v_cndmask_b32_e64 v179, 0, 1, vcc
	v_cmp_gt_i32_e32 vcc, s91, v178
	v_lshlrev_b32_e32 v178, 7, v178
	s_nop 0
	v_cndmask_b32_e32 v179, v179, v180, vcc
	v_and_b32_e32 v179, 1, v179
	v_cmp_eq_u32_e32 vcc, 1, v179
	v_add_u32_e32 v179, 0xbfff, v178
	v_mul_hi_i32 v180, v179, s96
	v_lshrrev_b32_e32 v181, 31, v180
	v_ashrrev_i32_e32 v180, 13, v180
	v_add_u32_e32 v180, v180, v181
	s_and_b64 s[16:17], s[8:9], vcc
	v_mul_i32_i24_e32 v180, 0xc000, v180
	v_cndmask_b32_e64 v182, 1.0, 0, s[16:17]
	s_and_b64 s[16:17], s[6:7], vcc
	v_sub_u32_e32 v179, v179, v180
	v_cndmask_b32_e64 v180, 1.0, 0, s[16:17]
	s_andn2_b64 s[16:17], s[36:37], exec
	v_cndmask_b32_e64 v178, v178, v179, s[6:7]
	s_or_b64 s[82:83], s[16:17], s[20:21]
;     __device__ __forceinline__ void operator()(const f32x4 (&acc)[2][2][4][2], const Unit& u, int wr, int wc, int fr, int fq) const {
;     ...
;         for (int ai = 0; ai < 2; ++ai)
; #pragma unroll
;             for (int m = 0; m < 4; ++m) {
;                 bool valid; int grow; bool zp = false, zn = false;
;                 if (!fix) { valid = !((ai == 0 && m == 0 && fr == 0) || (ai == 1 && m == 3 && fr == 15)); grow = u.pm * BM + wr * HALF + ai * 64 + m * 16 + fr; }
;                 else { const int R = (u.pm - nmain) * BM + wr * HALF + ai * 64 + m * 16 + fr; const int grp = R >> 2, pos = R & 3;
;                     const bool ss = (grp < 256) ? ((grp & 15) == 0) : (grp == 256);
;                     valid = (pos == 1) || (pos == 2); grow = (pos == 1) ? ((grp * 128 - 1 + mrows) % mrows) : (grp * 128);
;                     zn = (pos == 1) && ss; zp = (pos == 2) && ss; }
;                 f32x4 res[2];
;                 const float fzp = zp ? 0.f : 1.f, fzn = zn ? 0.f : 1.f;
; #pragma unroll
;                 for (int n = 0; n < 2; ++n) {
;                     const f32x4 g = acc[ai][0][m][n], up = acc[ai][1][m][n];
;                     f32x4 tp = g, tn = g;
;                     if (!fix) { const f32x4 gm = (m > 0) ? acc[ai][0][m - 1][n] : acc[ai ^ 1][0][3][n], gx = (m < 3) ? acc[ai][0][m + 1][n] : acc[ai ^ 1][0][0][n];
;                         tp = (fr == 15) ? gm : g; tn = (fr == 0) ? gx : g; }
;                     f32x4 gp, gn;
; #pragma unroll
;                     for (int j = 0; j < 4; ++j) { gp[j] = dpp_ror1(tp[j]); gn[j] = dpp_ror15(tn[j]); }
;                     const f32x4 cv = (w0[n] * fzp) * gp + (w1[n] * g + ((w2[n] * fzn) * gn + bb[n]));
;                     const f32x4 inner = cv * (cv * cv * 0.044715f + 1.0f) * (-2.0f * 0.7978845608028654f * 1.4426950408889634f);
;                     f32x4 sg;
; #pragma unroll
;                     for (int j = 0; j < 4; ++j) sg[j] = __builtin_amdgcn_rcpf(1.0f + __builtin_amdgcn_exp2f(inner[j]));
;                     res[n] = cv * sg * up;
;                 }
;                 if (valid) { u32x4 w; w.x = cvt_pk_bf16(res[0][0], res[0][1]); w.y = cvt_pk_bf16(res[0][2], res[0][3]); w.z = cvt_pk_bf16(res[1][0], res[1][1]); w.w = cvt_pk_bf16(res[1][2], res[1][3]);
;                     __builtin_nontemporal_store(w, (u32x4*)(ACT + (size_t)grow * 4096 + ch0)); }
.LBB0_631:
	s_and_b64 s[16:17], s[0:1], s[18:19]
	s_and_b64 s[18:19], s[4:5], s[18:19]
	v_cndmask_b32_e64 v188, v36, v140, s[18:19]
	v_cndmask_b32_e64 v184, v36, v12, s[16:17]
	v_cndmask_b32_e64 v185, v39, v143, s[18:19]
	v_cndmask_b32_e64 v186, v38, v142, s[18:19]
	v_cndmask_b32_e64 v187, v37, v141, s[18:19]
	v_mov_b32_dpp v196, v188 row_ror:15 row_mask:0xf bank_mask:0xf
	v_cndmask_b32_e64 v189, v28, v136, s[18:19]
	v_cndmask_b32_e64 v179, v39, v15, s[16:17]
	v_cndmask_b32_e64 v181, v38, v14, s[16:17]
	v_cndmask_b32_e64 v183, v37, v13, s[16:17]
	v_mov_b32_dpp v192, v184 row_ror:1 row_mask:0xf bank_mask:0xf
	v_mov_b32_dpp v197, v187 row_ror:15 row_mask:0xf bank_mask:0xf
	v_mov_b32_dpp v198, v186 row_ror:15 row_mask:0xf bank_mask:0xf
	v_mov_b32_dpp v199, v185 row_ror:15 row_mask:0xf bank_mask:0xf
	v_cndmask_b32_e64 v185, v28, v8, s[16:17]
	v_cndmask_b32_e64 v187, v30, v138, s[18:19]
	v_cndmask_b32_e64 v186, v29, v137, s[18:19]
	v_mov_b32_dpp v188, v189 row_ror:15 row_mask:0xf bank_mask:0xf
	v_mov_b32_dpp v193, v183 row_ror:1 row_mask:0xf bank_mask:0xf
	v_mov_b32_dpp v194, v181 row_ror:1 row_mask:0xf bank_mask:0xf
	v_mov_b32_dpp v195, v179 row_ror:1 row_mask:0xf bank_mask:0xf
	v_cndmask_b32_e64 v179, v31, v11, s[16:17]
	v_cndmask_b32_e64 v181, v30, v10, s[16:17]
	v_cndmask_b32_e64 v183, v29, v9, s[16:17]
	v_cndmask_b32_e64 v212, v31, v139, s[18:19]
	v_mov_b32_dpp v184, v185 row_ror:1 row_mask:0xf bank_mask:0xf
	v_mov_b32_dpp v189, v186 row_ror:15 row_mask:0xf bank_mask:0xf
	v_mov_b32_dpp v190, v187 row_ror:15 row_mask:0xf bank_mask:0xf
	v_mov_b32_dpp v185, v183 row_ror:1 row_mask:0xf bank_mask:0xf
	v_mov_b32_dpp v186, v181 row_ror:1 row_mask:0xf bank_mask:0xf
	v_mov_b32_dpp v187, v179 row_ror:1 row_mask:0xf bank_mask:0xf
	v_mov_b32_dpp v191, v212 row_ror:15 row_mask:0xf bank_mask:0xf
	s_waitcnt lgkmcnt(0)
	s_and_saveexec_b64 s[20:21], s[82:83]
	s_cbranch_execz .LBB0_633
	v_pk_mul_f32 v[218:219], v[96:97], v[180:181] op_sel_hi:[1,0]
	v_pk_mul_f32 v[214:215], v[88:89], v[182:183] op_sel_hi:[1,0]
	v_pk_fma_f32 v[196:197], v[218:219], v[196:197], v[100:101]
	v_pk_mul_f32 v[216:217], v[98:99], v[180:181] op_sel_hi:[1,0]
	v_pk_fma_f32 v[196:197], v[36:37], v[92:93], v[196:197]
	v_pk_fma_f32 v[198:199], v[216:217], v[198:199], v[102:103]
	v_pk_fma_f32 v[192:193], v[214:215], v[192:193], v[196:197]
	v_pk_mul_f32 v[212:213], v[90:91], v[182:183] op_sel_hi:[1,0]
	v_pk_mul_f32 v[196:197], v[192:193], v[192:193]
	v_pk_fma_f32 v[198:199], v[38:39], v[94:95], v[198:199]
	v_fma_f32 v179, v196, s97, 1.0
	v_mul_f32_e32 v179, v192, v179
	v_mul_f32_e32 v179, 0xc0135761, v179
	v_exp_f32_e32 v179, v179
	v_pk_fma_f32 v[194:195], v[212:213], v[194:195], v[198:199]
	v_add_f32_e32 v179, 1.0, v179
	v_pk_mul_f32 v[198:199], v[194:195], v[194:195]
	v_rcp_f32_e32 v196, v179
	v_fma_f32 v181, v198, s97, 1.0
	v_mul_f32_e32 v181, v194, v181
	v_fma_f32 v183, v199, s97, 1.0
	v_mul_f32_e32 v181, 0xc0135761, v181
	v_mul_f32_e32 v183, v195, v183
	v_fma_f32 v179, v197, s97, 1.0
	v_exp_f32_e32 v181, v181
	v_mul_f32_e32 v183, 0xc0135761, v183
	v_mul_f32_e32 v179, v193, v179
	v_exp_f32_e32 v183, v183
	v_mul_f32_e32 v179, 0xc0135761, v179
	v_exp_f32_e32 v179, v179
	v_add_f32_e32 v181, 1.0, v181
	v_rcp_f32_e32 v198, v181
	v_add_f32_e32 v181, 1.0, v183
	v_rcp_f32_e32 v199, v181
	v_add_f32_e32 v179, 1.0, v179
	v_rcp_f32_e32 v197, v179
	v_pk_mul_f32 v[194:195], v[194:195], v[198:199]
	v_pk_mul_f32 v[198:199], v[82:83], v[180:181] op_sel_hi:[1,0]
	v_pk_mul_f32 v[180:181], v[80:81], v[180:181] op_sel_hi:[1,0]
	v_pk_mul_f32 v[192:193], v[192:193], v[196:197]
	v_pk_fma_f32 v[180:181], v[180:181], v[188:189], v[84:85]
	v_pk_mul_f32 v[196:197], v[74:75], v[182:183] op_sel_hi:[1,0]
	v_pk_mul_f32 v[182:183], v[72:73], v[182:183] op_sel_hi:[1,0]
	v_pk_fma_f32 v[180:181], v[28:29], v[76:77], v[180:181]
	v_pk_fma_f32 v[190:191], v[198:199], v[190:191], v[86:87]
	v_pk_fma_f32 v[180:181], v[182:183], v[184:185], v[180:181]
	v_pk_fma_f32 v[184:185], v[30:31], v[78:79], v[190:191]
	v_pk_mul_f32 v[182:183], v[180:181], v[180:181]
	v_pk_fma_f32 v[184:185], v[196:197], v[186:187], v[184:185]
	v_fma_f32 v179, v182, s97, 1.0
	v_mul_f32_e32 v179, v180, v179
	v_mul_f32_e32 v179, 0xc0135761, v179
	v_exp_f32_e32 v179, v179
	v_pk_mul_f32 v[186:187], v[184:185], v[184:185]
	v_pk_mul_f32 v[156:157], v[156:157], v[192:193]
	v_pk_mul_f32 v[158:159], v[158:159], v[194:195]
	v_add_f32_e32 v179, 1.0, v179
	v_rcp_f32_e32 v182, v179
	v_fma_f32 v179, v183, s97, 1.0
	v_fma_f32 v183, v186, s97, 1.0
	v_mul_f32_e32 v183, v184, v183
	v_fma_f32 v186, v187, s97, 1.0
	v_mul_f32_e32 v179, v181, v179
	v_mul_f32_e32 v183, 0xc0135761, v183
	v_mul_f32_e32 v186, v185, v186
	v_mul_f32_e32 v179, 0xc0135761, v179
	v_exp_f32_e32 v183, v183
	v_mul_f32_e32 v186, 0xc0135761, v186
	v_exp_f32_e32 v179, v179
	v_exp_f32_e32 v187, v186
	v_add_f32_e32 v183, 1.0, v183
	v_rcp_f32_e32 v186, v183
	v_add_f32_e32 v179, 1.0, v179
	v_add_f32_e32 v183, 1.0, v187
	v_rcp_f32_e32 v187, v183
	v_rcp_f32_e32 v183, v179
	v_ashrrev_i32_e32 v179, 31, v178
	v_pk_mul_f32 v[184:185], v[184:185], v[186:187]
	v_pk_mul_f32 v[180:181], v[180:181], v[182:183]
	v_pk_mul_f32 v[182:183], v[154:155], v[184:185]
	v_pk_mul_f32 v[154:155], v[152:153], v[180:181]
	v_cvt_pk_bf16_f32 v152, v156, v157
	v_lshlrev_b64 v[156:157], 13, v[178:179]
	v_lshl_add_u64 v[156:157], s[44:45], 0, v[156:157]
	v_lshl_add_u64 v[156:157], v[176:177], 1, v[156:157]
	v_cvt_pk_bf16_f32 v153, v158, v159
	v_cvt_pk_bf16_f32 v154, v154, v155
	v_cvt_pk_bf16_f32 v155, v182, v183
	global_store_dwordx4 v[156:157], v[152:155], off nt
